# P1 epilogue: LDS transpose read-back into fresh regs, global stores deferred one piece (software-pipelined LDS round trip)
# baseline (speedup 1.0000x reference)
; #define PG8_LAS __attribute__((address_space(3)))
; __device__ __forceinline__ size_t tm_block(int pm, int ct, int nct) { return ((size_t)pm * nct + ct) * 32768; }
; __device__ __forceinline__ u32x4 pack8(const f32x4& v0, const f32x4& v1) { u32x4 w; w.x = cvt_pk_bf16(v0[0], v0[1]); w.y = cvt_pk_bf16(v0[2], v0[3]); w.z = cvt_pk_bf16(v1[0], v1[1]); w.w = cvt_pk_bf16(v1[2], v1[3]); return w; }
;     template <bool NT> __device__ __forceinline__ void flush(int ai, int m) const {
;         const u32x4 r0 = *(const PG8_LAS u32x4*)rp, r1 = *(const PG8_LAS u32x4*)(rp + 8 * PG8_SCR_STRIDE);
;         u32x4* p = (u32x4*)(ob + ai * 16384 + m * 2048);
;         if (NT) { __builtin_nontemporal_store(r0, p); __builtin_nontemporal_store(r1, p + 64); } else { *p = r0; *(p + 64) = r1; } }
;     __device__ __forceinline__ void operator()(const f32x4 (&acc)[2][2][4][2], const Unit& u, int wr, int wc, int fr, int fq) const {
;         const PieceOut po(scr, O, tm_block(u.pm, u.pn * 4 + wc, nct), wr, wc, fr, fq);
;         const float qs = (u.pn < 2 || u.pn == 3 || u.pn == 4) ? 0.125f * 1.4426950408889634f : 1.0f;
; #pragma unroll
;         for (int ai = 0; ai < 2; ++ai)
; #pragma unroll
;             for (int m = 0; m < 4; ++m) { po.put(0, pack8(acc[ai][0][m][0] * qs, acc[ai][0][m][1] * qs)); po.put(1, pack8(acc[ai][1][m][0] * qs, acc[ai][1][m][1] * qs)); po.flush<true>(ai, m); }
.LBB0_153:
	s_lshl_b32 s15, s70, 2
	s_or_b32 s15, s15, s53
	s_mul_hi_i32 s17, s22, 0x44
	s_mulk_i32 s22, 0x44
	s_ashr_i32 s25, s15, 31
	s_add_u32 s24, s22, s15
	s_addc_u32 s25, s17, s25
	s_lshl_b64 s[24:25], s[24:25], 15
	s_cmp_lt_i32 s70, 2
	s_cselect_b64 s[26:27], -1, 0
	s_add_i32 s15, s70, -3
	s_cmp_lt_u32 s15, 2
	s_cselect_b64 s[28:29], -1, 0
	s_or_b64 vcc, s[26:27], s[28:29]
	v_cndmask_b32_e32 v148, 1.0, v155, vcc
	v_pk_mul_f32 v[128:129], v[148:149], v[128:129] op_sel_hi:[0,1]
	v_pk_mul_f32 v[126:127], v[148:149], v[126:127] op_sel_hi:[0,1]
	v_pk_mul_f32 v[156:157], v[148:149], v[124:125] op_sel_hi:[0,1]
	v_pk_mul_f32 v[124:125], v[148:149], v[122:123] op_sel_hi:[0,1]
	v_cvt_pk_bf16_f32 v122, v126, v127
	v_cvt_pk_bf16_f32 v123, v128, v129
	v_cvt_pk_bf16_f32 v124, v124, v125
	v_cvt_pk_bf16_f32 v125, v156, v157
	ds_write_b128 v153, v[122:125]
	v_pk_mul_f32 v[122:123], v[148:149], v[112:113] op_sel_hi:[0,1]
	v_pk_mul_f32 v[112:113], v[148:149], v[110:111] op_sel_hi:[0,1]
	v_pk_mul_f32 v[120:121], v[148:149], v[120:121] op_sel_hi:[0,1]
	v_pk_mul_f32 v[118:119], v[148:149], v[118:119] op_sel_hi:[0,1]
	v_cvt_pk_bf16_f32 v110, v118, v119
	v_cvt_pk_bf16_f32 v111, v120, v121
	v_cvt_pk_bf16_f32 v112, v112, v113
	v_cvt_pk_bf16_f32 v113, v122, v123
	ds_write_b128 v153, v[110:113] offset:64
	ds_read_b128 v[160:163], v154
	ds_read_b128 v[164:167], v154 offset:1152
	v_lshl_add_u64 v[122:123], v[138:139], 0, s[24:25]
	v_pk_mul_f32 v[110:111], v[148:149], v[116:117] op_sel_hi:[0,1]
	v_pk_mul_f32 v[112:113], v[148:149], v[114:115] op_sel_hi:[0,1]
	v_pk_mul_f32 v[114:115], v[148:149], v[108:109] op_sel_hi:[0,1]
	v_pk_mul_f32 v[108:109], v[148:149], v[106:107] op_sel_hi:[0,1]
	v_cvt_pk_bf16_f32 v106, v112, v113
	v_cvt_pk_bf16_f32 v107, v110, v111
	v_cvt_pk_bf16_f32 v108, v108, v109
	v_cvt_pk_bf16_f32 v109, v114, v115
	ds_write_b128 v153, v[106:109]
	v_pk_mul_f32 v[106:107], v[148:149], v[96:97] op_sel_hi:[0,1]
	v_pk_mul_f32 v[96:97], v[148:149], v[94:95] op_sel_hi:[0,1]
	v_pk_mul_f32 v[104:105], v[148:149], v[104:105] op_sel_hi:[0,1]
	v_pk_mul_f32 v[102:103], v[148:149], v[102:103] op_sel_hi:[0,1]
	v_cvt_pk_bf16_f32 v94, v102, v103
	v_cvt_pk_bf16_f32 v95, v104, v105
	v_cvt_pk_bf16_f32 v96, v96, v97
	v_cvt_pk_bf16_f32 v97, v106, v107
	ds_write_b128 v153, v[94:97] offset:64
	s_waitcnt lgkmcnt(2)
	global_store_dwordx4 v[122:123], v[160:163], off nt
	global_store_dwordx4 v[122:123], v[164:167], off offset:1024 nt
	ds_read_b128 v[168:171], v154
	ds_read_b128 v[172:175], v154 offset:1152
	v_pk_mul_f32 v[94:95], v[148:149], v[100:101] op_sel_hi:[0,1]
	v_pk_mul_f32 v[96:97], v[148:149], v[98:99] op_sel_hi:[0,1]
	v_pk_mul_f32 v[98:99], v[148:149], v[92:93] op_sel_hi:[0,1]
	v_pk_mul_f32 v[92:93], v[148:149], v[90:91] op_sel_hi:[0,1]
	v_cvt_pk_bf16_f32 v90, v96, v97
	v_cvt_pk_bf16_f32 v91, v94, v95
	v_cvt_pk_bf16_f32 v92, v92, v93
	v_cvt_pk_bf16_f32 v93, v98, v99
	ds_write_b128 v153, v[90:93]
	v_pk_mul_f32 v[90:91], v[148:149], v[84:85] op_sel_hi:[0,1]
	v_pk_mul_f32 v[84:85], v[148:149], v[82:83] op_sel_hi:[0,1]
	v_pk_mul_f32 v[88:89], v[148:149], v[88:89] op_sel_hi:[0,1]
	v_pk_mul_f32 v[86:87], v[148:149], v[86:87] op_sel_hi:[0,1]
	v_cvt_pk_bf16_f32 v82, v86, v87
	v_cvt_pk_bf16_f32 v83, v88, v89
	v_cvt_pk_bf16_f32 v84, v84, v85
	v_cvt_pk_bf16_f32 v85, v90, v91
	ds_write_b128 v153, v[82:85] offset:64
	s_waitcnt lgkmcnt(2)
	global_store_dwordx4 v[122:123], v[168:171], off offset:2048 nt
	global_store_dwordx4 v[122:123], v[172:175], off offset:3072 nt
	ds_read_b128 v[160:163], v154
	ds_read_b128 v[164:167], v154 offset:1152
	v_add_co_u32_e32 v90, vcc, s58, v122
	v_pk_mul_f32 v[80:81], v[148:149], v[80:81] op_sel_hi:[0,1]
	s_nop 0
	v_addc_co_u32_e32 v91, vcc, 0, v123, vcc
	v_pk_mul_f32 v[78:79], v[148:149], v[78:79] op_sel_hi:[0,1]
	v_pk_mul_f32 v[82:83], v[148:149], v[76:77] op_sel_hi:[0,1]
	v_pk_mul_f32 v[76:77], v[148:149], v[74:75] op_sel_hi:[0,1]
	v_cvt_pk_bf16_f32 v74, v78, v79
	v_cvt_pk_bf16_f32 v75, v80, v81
	v_cvt_pk_bf16_f32 v76, v76, v77
	v_cvt_pk_bf16_f32 v77, v82, v83
	ds_write_b128 v153, v[74:77]
	v_pk_mul_f32 v[74:75], v[148:149], v[68:69] op_sel_hi:[0,1]
	v_pk_mul_f32 v[68:69], v[148:149], v[66:67] op_sel_hi:[0,1]
	v_pk_mul_f32 v[72:73], v[148:149], v[72:73] op_sel_hi:[0,1]
	v_pk_mul_f32 v[70:71], v[148:149], v[70:71] op_sel_hi:[0,1]
	v_cvt_pk_bf16_f32 v66, v70, v71
	v_cvt_pk_bf16_f32 v67, v72, v73
	v_cvt_pk_bf16_f32 v68, v68, v69
	v_cvt_pk_bf16_f32 v69, v74, v75
	ds_write_b128 v153, v[66:69] offset:64
	s_waitcnt lgkmcnt(2)
; #define PG8_LAS __attribute__((address_space(3)))
; __device__ __forceinline__ u32x4 pack8(const f32x4& v0, const f32x4& v1) { u32x4 w; w.x = cvt_pk_bf16(v0[0], v0[1]); w.y = cvt_pk_bf16(v0[2], v0[3]); w.z = cvt_pk_bf16(v1[0], v1[1]); w.w = cvt_pk_bf16(v1[2], v1[3]); return w; }
;     template <bool NT> __device__ __forceinline__ void flush(int ai, int m) const {
;         const u32x4 r0 = *(const PG8_LAS u32x4*)rp, r1 = *(const PG8_LAS u32x4*)(rp + 8 * PG8_SCR_STRIDE);
;         u32x4* p = (u32x4*)(ob + ai * 16384 + m * 2048);
;         if (NT) { __builtin_nontemporal_store(r0, p); __builtin_nontemporal_store(r1, p + 64); } else { *p = r0; *(p + 64) = r1; } }
;     __device__ __forceinline__ void operator()(const f32x4 (&acc)[2][2][4][2], const Unit& u, int wr, int wc, int fr, int fq) const {
;     ...
;         for (int ai = 0; ai < 2; ++ai)
; #pragma unroll
;             for (int m = 0; m < 4; ++m) { po.put(0, pack8(acc[ai][0][m][0] * qs, acc[ai][0][m][1] * qs)); po.put(1, pack8(acc[ai][1][m][0] * qs, acc[ai][1][m][1] * qs)); po.flush<true>(ai, m); }
	global_store_dwordx4 v[90:91], v[160:163], off nt
	global_store_dwordx4 v[90:91], v[164:167], off offset:1024 nt
	ds_read_b128 v[168:171], v154
	ds_read_b128 v[172:175], v154 offset:1152
	v_pk_mul_f32 v[64:65], v[148:149], v[64:65] op_sel_hi:[0,1]
	v_pk_mul_f32 v[62:63], v[148:149], v[62:63] op_sel_hi:[0,1]
	v_pk_mul_f32 v[66:67], v[148:149], v[60:61] op_sel_hi:[0,1]
	v_pk_mul_f32 v[60:61], v[148:149], v[58:59] op_sel_hi:[0,1]
	v_cvt_pk_bf16_f32 v58, v62, v63
	v_cvt_pk_bf16_f32 v59, v64, v65
	v_cvt_pk_bf16_f32 v60, v60, v61
	v_cvt_pk_bf16_f32 v61, v66, v67
	ds_write_b128 v153, v[58:61]
	v_pk_mul_f32 v[58:59], v[148:149], v[52:53] op_sel_hi:[0,1]
	v_pk_mul_f32 v[52:53], v[148:149], v[50:51] op_sel_hi:[0,1]
	v_pk_mul_f32 v[56:57], v[148:149], v[56:57] op_sel_hi:[0,1]
	v_pk_mul_f32 v[54:55], v[148:149], v[54:55] op_sel_hi:[0,1]
	v_cvt_pk_bf16_f32 v50, v54, v55
	v_cvt_pk_bf16_f32 v51, v56, v57
	v_cvt_pk_bf16_f32 v52, v52, v53
	v_cvt_pk_bf16_f32 v53, v58, v59
	ds_write_b128 v153, v[50:53] offset:64
	s_waitcnt lgkmcnt(2)
	global_store_dwordx4 v[90:91], v[168:171], off offset:2048 nt
	global_store_dwordx4 v[90:91], v[172:175], off offset:3072 nt
	ds_read_b128 v[160:163], v154
	ds_read_b128 v[164:167], v154 offset:1152
	v_add_co_u32_e32 v58, vcc, s52, v122
	v_pk_mul_f32 v[48:49], v[148:149], v[48:49] op_sel_hi:[0,1]
	s_nop 0
	v_addc_co_u32_e32 v59, vcc, 0, v123, vcc
	v_add_co_u32_e32 v60, vcc, s59, v122
	v_pk_mul_f32 v[46:47], v[148:149], v[46:47] op_sel_hi:[0,1]
	s_nop 0
	v_addc_co_u32_e32 v61, vcc, 0, v123, vcc
	v_pk_mul_f32 v[40:41], v[148:149], v[40:41] op_sel_hi:[0,1]
	v_pk_mul_f32 v[50:51], v[148:149], v[44:45] op_sel_hi:[0,1]
	v_pk_mul_f32 v[44:45], v[148:149], v[42:43] op_sel_hi:[0,1]
	v_cvt_pk_bf16_f32 v42, v46, v47
	v_cvt_pk_bf16_f32 v43, v48, v49
	v_cvt_pk_bf16_f32 v44, v44, v45
	v_cvt_pk_bf16_f32 v45, v50, v51
	ds_write_b128 v153, v[42:45]
	v_pk_mul_f32 v[42:43], v[148:149], v[32:33] op_sel_hi:[0,1]
	v_pk_mul_f32 v[32:33], v[148:149], v[30:31] op_sel_hi:[0,1]
	v_pk_mul_f32 v[38:39], v[148:149], v[38:39] op_sel_hi:[0,1]
	v_cvt_pk_bf16_f32 v30, v38, v39
	v_cvt_pk_bf16_f32 v31, v40, v41
	v_cvt_pk_bf16_f32 v32, v32, v33
	v_cvt_pk_bf16_f32 v33, v42, v43
	ds_write_b128 v153, v[30:33] offset:64
	s_waitcnt lgkmcnt(2)
	global_store_dwordx4 v[60:61], v[160:163], off offset:-4096 nt
	global_store_dwordx4 v[58:59], v[164:167], off offset:1024 nt
	ds_read_b128 v[168:171], v154
	ds_read_b128 v[172:175], v154 offset:1152
	v_pk_mul_f32 v[30:31], v[148:149], v[36:37] op_sel_hi:[0,1]
	v_pk_mul_f32 v[32:33], v[148:149], v[34:35] op_sel_hi:[0,1]
	v_pk_mul_f32 v[34:35], v[148:149], v[28:29] op_sel_hi:[0,1]
	v_pk_mul_f32 v[28:29], v[148:149], v[26:27] op_sel_hi:[0,1]
	v_cvt_pk_bf16_f32 v26, v32, v33
	v_cvt_pk_bf16_f32 v27, v30, v31
	v_cvt_pk_bf16_f32 v28, v28, v29
	v_cvt_pk_bf16_f32 v29, v34, v35
	ds_write_b128 v153, v[26:29]
	v_pk_mul_f32 v[26:27], v[148:149], v[16:17] op_sel_hi:[0,1]
	v_pk_mul_f32 v[16:17], v[148:149], v[14:15] op_sel_hi:[0,1]
	v_pk_mul_f32 v[24:25], v[148:149], v[24:25] op_sel_hi:[0,1]
	v_pk_mul_f32 v[22:23], v[148:149], v[22:23] op_sel_hi:[0,1]
	v_cvt_pk_bf16_f32 v14, v22, v23
	v_cvt_pk_bf16_f32 v15, v24, v25
	v_cvt_pk_bf16_f32 v16, v16, v17
	v_cvt_pk_bf16_f32 v17, v26, v27
	ds_write_b128 v153, v[14:17] offset:64
	s_waitcnt lgkmcnt(2)
	global_store_dwordx4 v[58:59], v[168:171], off offset:2048 nt
	global_store_dwordx4 v[58:59], v[172:175], off offset:3072 nt
	ds_read_b128 v[160:163], v154
	ds_read_b128 v[164:167], v154 offset:1152
	v_pk_mul_f32 v[14:15], v[148:149], v[20:21] op_sel_hi:[0,1]
	v_pk_mul_f32 v[16:17], v[148:149], v[18:19] op_sel_hi:[0,1]
	v_pk_mul_f32 v[18:19], v[148:149], v[12:13] op_sel_hi:[0,1]
	v_pk_mul_f32 v[12:13], v[148:149], v[10:11] op_sel_hi:[0,1]
	v_cvt_pk_bf16_f32 v10, v16, v17
	v_cvt_pk_bf16_f32 v11, v14, v15
	v_cvt_pk_bf16_f32 v12, v12, v13
	v_cvt_pk_bf16_f32 v13, v18, v19
	ds_write_b128 v153, v[10:13]
	v_pk_mul_f32 v[10:11], v[148:149], v[4:5] op_sel_hi:[0,1]
	v_pk_mul_f32 v[4:5], v[148:149], v[2:3] op_sel_hi:[0,1]
	v_pk_mul_f32 v[8:9], v[148:149], v[8:9] op_sel_hi:[0,1]
	v_pk_mul_f32 v[6:7], v[148:149], v[6:7] op_sel_hi:[0,1]
	v_cvt_pk_bf16_f32 v2, v6, v7
	v_cvt_pk_bf16_f32 v3, v8, v9
	v_cvt_pk_bf16_f32 v4, v4, v5
	v_cvt_pk_bf16_f32 v5, v10, v11
	ds_write_b128 v153, v[2:5] offset:64
	s_waitcnt lgkmcnt(2)
	global_store_dwordx4 v[60:61], v[160:163], off nt
	global_store_dwordx4 v[60:61], v[164:167], off offset:1024 nt
	ds_read_b128 v[168:171], v154
	ds_read_b128 v[172:175], v154 offset:1152
	s_andn2_b64 vcc, exec, s[4:5]
	s_mov_b64 s[4:5], -1
	s_waitcnt lgkmcnt(0)
	global_store_dwordx4 v[60:61], v[168:171], off offset:2048 nt
	global_store_dwordx4 v[60:61], v[172:175], off offset:3072 nt
	s_cbranch_vccnz .LBB0_146
	s_andn2_b64 vcc, exec, s[10:11]
	s_cbranch_vccnz .LBB0_145
	s_barrier
	s_branch .LBB0_145
